# stack1 + SwiGLU epilogue stage-interleaved over 8 elements (no chain nops, SGPR constant)
# baseline (speedup 1.0000x reference)
.LBB0_197:
	v_lshl_or_b32 v162, s21, 7, v144
	v_lshl_add_u32 v146, s20, 8, v142
	v_ashrrev_i32_e32 v163, 31, v162
	v_mov_b64_e32 v[140:141], s[8:9]
	v_mad_i64_i32 v[164:165], s[20:21], v146, s64, v[140:141]
	v_lshlrev_b64 v[166:167], 1, v[162:163]
	v_lshl_add_u64 v[164:165], v[164:165], 0, v[166:167]
	v_mul_f32_e32 v168, s65, v126
	v_mul_f32_e32 v169, s65, v127
	v_mul_f32_e32 v170, s65, v128
	v_mul_f32_e32 v171, s65, v129
	v_mul_f32_e32 v172, s65, v118
	v_mul_f32_e32 v173, s65, v119
	v_mul_f32_e32 v174, s65, v120
	v_mul_f32_e32 v175, s65, v121
	v_exp_f32_e32 v168, v168
	v_exp_f32_e32 v169, v169
	v_exp_f32_e32 v170, v170
	v_exp_f32_e32 v171, v171
	v_exp_f32_e32 v172, v172
	v_exp_f32_e32 v173, v173
	v_exp_f32_e32 v174, v174
	v_exp_f32_e32 v175, v175
	v_mul_f32_e32 v126, v126, v122
	v_mul_f32_e32 v127, v127, v123
	v_mul_f32_e32 v128, v128, v124
	v_mul_f32_e32 v129, v129, v125
	v_mul_f32_e32 v118, v118, v114
	v_mul_f32_e32 v119, v119, v115
	v_mul_f32_e32 v120, v120, v116
	v_mul_f32_e32 v121, v121, v117
	v_add_f32_e32 v168, 1.0, v168
	v_add_f32_e32 v169, 1.0, v169
	v_add_f32_e32 v170, 1.0, v170
	v_add_f32_e32 v171, 1.0, v171
	v_add_f32_e32 v172, 1.0, v172
	v_add_f32_e32 v173, 1.0, v173
	v_add_f32_e32 v174, 1.0, v174
	v_add_f32_e32 v175, 1.0, v175
	v_rcp_f32_e32 v168, v168
	v_rcp_f32_e32 v169, v169
	v_rcp_f32_e32 v170, v170
	v_rcp_f32_e32 v171, v171
	v_rcp_f32_e32 v172, v172
	v_rcp_f32_e32 v173, v173
	v_rcp_f32_e32 v174, v174
	v_rcp_f32_e32 v175, v175
	v_mul_f32_e32 v168, v126, v168
	v_mul_f32_e32 v169, v127, v169
	v_mul_f32_e32 v170, v128, v170
	v_mul_f32_e32 v171, v129, v171
	v_mul_f32_e32 v172, v118, v172
	v_mul_f32_e32 v173, v119, v173
	v_mul_f32_e32 v174, v120, v174
	v_mul_f32_e32 v175, v121, v175
	v_cvt_pk_bf16_f32 v184, v168, v169
	v_cvt_pk_bf16_f32 v185, v170, v171
	v_cvt_pk_bf16_f32 v186, v172, v173
	v_cvt_pk_bf16_f32 v187, v174, v175
	global_store_dwordx4 v[164:165], v[184:187], off
	s_mov_b64 s[20:21], 0x16000
	v_lshl_add_u64 v[194:195], v[164:165], 0, s[20:21]
	v_mul_f32_e32 v176, s65, v110
	v_mul_f32_e32 v177, s65, v111
	v_mul_f32_e32 v178, s65, v112
	v_mul_f32_e32 v179, s65, v113
	v_mul_f32_e32 v180, s65, v102
	v_mul_f32_e32 v181, s65, v103
	v_mul_f32_e32 v182, s65, v104
	v_mul_f32_e32 v183, s65, v105
	v_exp_f32_e32 v176, v176
	v_exp_f32_e32 v177, v177
	v_exp_f32_e32 v178, v178
	v_exp_f32_e32 v179, v179
	v_exp_f32_e32 v180, v180
	v_exp_f32_e32 v181, v181
	v_exp_f32_e32 v182, v182
	v_exp_f32_e32 v183, v183
	v_mul_f32_e32 v110, v110, v106
	v_mul_f32_e32 v111, v111, v107
	v_mul_f32_e32 v112, v112, v108
	v_mul_f32_e32 v113, v113, v109
	v_mul_f32_e32 v102, v102, v98
	v_mul_f32_e32 v103, v103, v99
	v_mul_f32_e32 v104, v104, v100
	v_mul_f32_e32 v105, v105, v101
	v_add_f32_e32 v176, 1.0, v176
	v_add_f32_e32 v177, 1.0, v177
	v_add_f32_e32 v178, 1.0, v178
	v_add_f32_e32 v179, 1.0, v179
	v_add_f32_e32 v180, 1.0, v180
	v_add_f32_e32 v181, 1.0, v181
	v_add_f32_e32 v182, 1.0, v182
	v_add_f32_e32 v183, 1.0, v183
	v_rcp_f32_e32 v176, v176
	v_rcp_f32_e32 v177, v177
	v_rcp_f32_e32 v178, v178
	v_rcp_f32_e32 v179, v179
	v_rcp_f32_e32 v180, v180
	v_rcp_f32_e32 v181, v181
	v_rcp_f32_e32 v182, v182
	v_rcp_f32_e32 v183, v183
	v_mul_f32_e32 v176, v110, v176
	v_mul_f32_e32 v177, v111, v177
	v_mul_f32_e32 v178, v112, v178
	v_mul_f32_e32 v179, v113, v179
	v_mul_f32_e32 v180, v102, v180
	v_mul_f32_e32 v181, v103, v181
	v_mul_f32_e32 v182, v104, v182
	v_mul_f32_e32 v183, v105, v183
	v_cvt_pk_bf16_f32 v188, v176, v177
	v_cvt_pk_bf16_f32 v189, v178, v179
	v_cvt_pk_bf16_f32 v190, v180, v181
	v_cvt_pk_bf16_f32 v191, v182, v183
	global_store_dwordx4 v[194:195], v[188:191], off
	s_mov_b64 s[20:21], 0x2c000
	v_lshl_add_u64 v[192:193], v[164:165], 0, s[20:21]
	v_mul_f32_e32 v168, s65, v94
	v_mul_f32_e32 v169, s65, v95
	v_mul_f32_e32 v170, s65, v96
	v_mul_f32_e32 v171, s65, v97
	v_mul_f32_e32 v172, s65, v86
	v_mul_f32_e32 v173, s65, v87
	v_mul_f32_e32 v174, s65, v88
	v_mul_f32_e32 v175, s65, v89
	v_exp_f32_e32 v168, v168
	v_exp_f32_e32 v169, v169
	v_exp_f32_e32 v170, v170
	v_exp_f32_e32 v171, v171
	v_exp_f32_e32 v172, v172
	v_exp_f32_e32 v173, v173
	v_exp_f32_e32 v174, v174
	v_exp_f32_e32 v175, v175
	v_mul_f32_e32 v94, v94, v90
	v_mul_f32_e32 v95, v95, v91
	v_mul_f32_e32 v96, v96, v92
	v_mul_f32_e32 v97, v97, v93
	v_mul_f32_e32 v86, v86, v82
	v_mul_f32_e32 v87, v87, v83
	v_mul_f32_e32 v88, v88, v84
	v_mul_f32_e32 v89, v89, v85
	v_add_f32_e32 v168, 1.0, v168
	v_add_f32_e32 v169, 1.0, v169
	v_add_f32_e32 v170, 1.0, v170
	v_add_f32_e32 v171, 1.0, v171
	v_add_f32_e32 v172, 1.0, v172
	v_add_f32_e32 v173, 1.0, v173
	v_add_f32_e32 v174, 1.0, v174
	v_add_f32_e32 v175, 1.0, v175
	v_rcp_f32_e32 v168, v168
	v_rcp_f32_e32 v169, v169
	v_rcp_f32_e32 v170, v170
	v_rcp_f32_e32 v171, v171
	v_rcp_f32_e32 v172, v172
	v_rcp_f32_e32 v173, v173
	v_rcp_f32_e32 v174, v174
	v_rcp_f32_e32 v175, v175
	v_mul_f32_e32 v168, v94, v168
	v_mul_f32_e32 v169, v95, v169
	v_mul_f32_e32 v170, v96, v170
	v_mul_f32_e32 v171, v97, v171
	v_mul_f32_e32 v172, v86, v172
	v_mul_f32_e32 v173, v87, v173
	v_mul_f32_e32 v174, v88, v174
	v_mul_f32_e32 v175, v89, v175
	v_cvt_pk_bf16_f32 v184, v168, v169
	v_cvt_pk_bf16_f32 v185, v170, v171
	v_cvt_pk_bf16_f32 v186, v172, v173
	v_cvt_pk_bf16_f32 v187, v174, v175
	global_store_dwordx4 v[192:193], v[184:187], off
	s_mov_b64 s[20:21], 0x42000
	v_lshl_add_u64 v[194:195], v[164:165], 0, s[20:21]
	v_mul_f32_e32 v176, s65, v78
	v_mul_f32_e32 v177, s65, v79
	v_mul_f32_e32 v178, s65, v80
	v_mul_f32_e32 v179, s65, v81
	v_mul_f32_e32 v180, s65, v70
	v_mul_f32_e32 v181, s65, v71
	v_mul_f32_e32 v182, s65, v72
	v_mul_f32_e32 v183, s65, v73
	v_exp_f32_e32 v176, v176
	v_exp_f32_e32 v177, v177
	v_exp_f32_e32 v178, v178
	v_exp_f32_e32 v179, v179
	v_exp_f32_e32 v180, v180
	v_exp_f32_e32 v181, v181
	v_exp_f32_e32 v182, v182
	v_exp_f32_e32 v183, v183
	v_mul_f32_e32 v78, v78, v74
	v_mul_f32_e32 v79, v79, v75
	v_mul_f32_e32 v80, v80, v76
	v_mul_f32_e32 v81, v81, v77
	v_mul_f32_e32 v70, v70, v66
	v_mul_f32_e32 v71, v71, v67
	v_mul_f32_e32 v72, v72, v68
	v_mul_f32_e32 v73, v73, v69
	v_add_f32_e32 v176, 1.0, v176
	v_add_f32_e32 v177, 1.0, v177
	v_add_f32_e32 v178, 1.0, v178
	v_add_f32_e32 v179, 1.0, v179
	v_add_f32_e32 v180, 1.0, v180
	v_add_f32_e32 v181, 1.0, v181
	v_add_f32_e32 v182, 1.0, v182
	v_add_f32_e32 v183, 1.0, v183
	v_rcp_f32_e32 v176, v176
	v_rcp_f32_e32 v177, v177
	v_rcp_f32_e32 v178, v178
	v_rcp_f32_e32 v179, v179
	v_rcp_f32_e32 v180, v180
	v_rcp_f32_e32 v181, v181
	v_rcp_f32_e32 v182, v182
	v_rcp_f32_e32 v183, v183
	v_mul_f32_e32 v176, v78, v176
	v_mul_f32_e32 v177, v79, v177
	v_mul_f32_e32 v178, v80, v178
	v_mul_f32_e32 v179, v81, v179
	v_mul_f32_e32 v180, v70, v180
	v_mul_f32_e32 v181, v71, v181
	v_mul_f32_e32 v182, v72, v182
	v_mul_f32_e32 v183, v73, v183
	v_cvt_pk_bf16_f32 v188, v176, v177
	v_cvt_pk_bf16_f32 v189, v178, v179
	v_cvt_pk_bf16_f32 v190, v180, v181
	v_cvt_pk_bf16_f32 v191, v182, v183
	global_store_dwordx4 v[194:195], v[188:191], off
	s_mov_b64 s[20:21], 0xb0000
	v_lshl_add_u64 v[192:193], v[164:165], 0, s[20:21]
	v_mul_f32_e32 v168, s65, v62
	v_mul_f32_e32 v169, s65, v63
	v_mul_f32_e32 v170, s65, v64
	v_mul_f32_e32 v171, s65, v65
	v_mul_f32_e32 v172, s65, v54
	v_mul_f32_e32 v173, s65, v55
	v_mul_f32_e32 v174, s65, v56
	v_mul_f32_e32 v175, s65, v57
	v_exp_f32_e32 v168, v168
	v_exp_f32_e32 v169, v169
	v_exp_f32_e32 v170, v170
	v_exp_f32_e32 v171, v171
	v_exp_f32_e32 v172, v172
	v_exp_f32_e32 v173, v173
	v_exp_f32_e32 v174, v174
	v_exp_f32_e32 v175, v175
	v_mul_f32_e32 v62, v62, v58
	v_mul_f32_e32 v63, v63, v59
	v_mul_f32_e32 v64, v64, v60
	v_mul_f32_e32 v65, v65, v61
	v_mul_f32_e32 v54, v54, v50
	v_mul_f32_e32 v55, v55, v51
	v_mul_f32_e32 v56, v56, v52
	v_mul_f32_e32 v57, v57, v53
	v_add_f32_e32 v168, 1.0, v168
	v_add_f32_e32 v169, 1.0, v169
	v_add_f32_e32 v170, 1.0, v170
	v_add_f32_e32 v171, 1.0, v171
	v_add_f32_e32 v172, 1.0, v172
	v_add_f32_e32 v173, 1.0, v173
	v_add_f32_e32 v174, 1.0, v174
	v_add_f32_e32 v175, 1.0, v175
	v_rcp_f32_e32 v168, v168
	v_rcp_f32_e32 v169, v169
	v_rcp_f32_e32 v170, v170
	v_rcp_f32_e32 v171, v171
	v_rcp_f32_e32 v172, v172
	v_rcp_f32_e32 v173, v173
	v_rcp_f32_e32 v174, v174
	v_rcp_f32_e32 v175, v175
	v_mul_f32_e32 v168, v62, v168
	v_mul_f32_e32 v169, v63, v169
	v_mul_f32_e32 v170, v64, v170
	v_mul_f32_e32 v171, v65, v171
	v_mul_f32_e32 v172, v54, v172
	v_mul_f32_e32 v173, v55, v173
	v_mul_f32_e32 v174, v56, v174
	v_mul_f32_e32 v175, v57, v175
	v_cvt_pk_bf16_f32 v184, v168, v169
	v_cvt_pk_bf16_f32 v185, v170, v171
	v_cvt_pk_bf16_f32 v186, v172, v173
	v_cvt_pk_bf16_f32 v187, v174, v175
	global_store_dwordx4 v[192:193], v[184:187], off
	s_mov_b64 s[20:21], 0xc6000
	v_lshl_add_u64 v[194:195], v[164:165], 0, s[20:21]
	v_mul_f32_e32 v176, s65, v46
	v_mul_f32_e32 v177, s65, v47
	v_mul_f32_e32 v178, s65, v48
	v_mul_f32_e32 v179, s65, v49
	v_mul_f32_e32 v180, s65, v38
	v_mul_f32_e32 v181, s65, v39
	v_mul_f32_e32 v182, s65, v40
	v_mul_f32_e32 v183, s65, v41
	v_exp_f32_e32 v176, v176
	v_exp_f32_e32 v177, v177
	v_exp_f32_e32 v178, v178
	v_exp_f32_e32 v179, v179
	v_exp_f32_e32 v180, v180
	v_exp_f32_e32 v181, v181
	v_exp_f32_e32 v182, v182
	v_exp_f32_e32 v183, v183
	v_mul_f32_e32 v46, v46, v42
	v_mul_f32_e32 v47, v47, v43
	v_mul_f32_e32 v48, v48, v44
	v_mul_f32_e32 v49, v49, v45
	v_mul_f32_e32 v38, v38, v34
	v_mul_f32_e32 v39, v39, v35
	v_mul_f32_e32 v40, v40, v36
	v_mul_f32_e32 v41, v41, v37
	v_add_f32_e32 v176, 1.0, v176
	v_add_f32_e32 v177, 1.0, v177
	v_add_f32_e32 v178, 1.0, v178
	v_add_f32_e32 v179, 1.0, v179
	v_add_f32_e32 v180, 1.0, v180
	v_add_f32_e32 v181, 1.0, v181
	v_add_f32_e32 v182, 1.0, v182
	v_add_f32_e32 v183, 1.0, v183
	v_rcp_f32_e32 v176, v176
	v_rcp_f32_e32 v177, v177
	v_rcp_f32_e32 v178, v178
	v_rcp_f32_e32 v179, v179
	v_rcp_f32_e32 v180, v180
	v_rcp_f32_e32 v181, v181
	v_rcp_f32_e32 v182, v182
	v_rcp_f32_e32 v183, v183
	v_mul_f32_e32 v176, v46, v176
	v_mul_f32_e32 v177, v47, v177
	v_mul_f32_e32 v178, v48, v178
	v_mul_f32_e32 v179, v49, v179
	v_mul_f32_e32 v180, v38, v180
	v_mul_f32_e32 v181, v39, v181
	v_mul_f32_e32 v182, v40, v182
	v_mul_f32_e32 v183, v41, v183
	v_cvt_pk_bf16_f32 v188, v176, v177
	v_cvt_pk_bf16_f32 v189, v178, v179
	v_cvt_pk_bf16_f32 v190, v180, v181
	v_cvt_pk_bf16_f32 v191, v182, v183
	global_store_dwordx4 v[194:195], v[188:191], off
	s_mov_b64 s[20:21], 0xdc000
	v_lshl_add_u64 v[192:193], v[164:165], 0, s[20:21]
	v_mul_f32_e32 v168, s65, v30
	v_mul_f32_e32 v169, s65, v31
	v_mul_f32_e32 v170, s65, v32
	v_mul_f32_e32 v171, s65, v33
	v_mul_f32_e32 v172, s65, v22
	v_mul_f32_e32 v173, s65, v23
	v_mul_f32_e32 v174, s65, v24
	v_mul_f32_e32 v175, s65, v25
	v_exp_f32_e32 v168, v168
	v_exp_f32_e32 v169, v169
	v_exp_f32_e32 v170, v170
	v_exp_f32_e32 v171, v171
	v_exp_f32_e32 v172, v172
	v_exp_f32_e32 v173, v173
	v_exp_f32_e32 v174, v174
	v_exp_f32_e32 v175, v175
	v_mul_f32_e32 v30, v30, v26
	v_mul_f32_e32 v31, v31, v27
	v_mul_f32_e32 v32, v32, v28
	v_mul_f32_e32 v33, v33, v29
	v_mul_f32_e32 v22, v22, v18
	v_mul_f32_e32 v23, v23, v19
	v_mul_f32_e32 v24, v24, v20
	v_mul_f32_e32 v25, v25, v21
	v_add_f32_e32 v168, 1.0, v168
	v_add_f32_e32 v169, 1.0, v169
	v_add_f32_e32 v170, 1.0, v170
	v_add_f32_e32 v171, 1.0, v171
	v_add_f32_e32 v172, 1.0, v172
	v_add_f32_e32 v173, 1.0, v173
	v_add_f32_e32 v174, 1.0, v174
	v_add_f32_e32 v175, 1.0, v175
	v_rcp_f32_e32 v168, v168
	v_rcp_f32_e32 v169, v169
	v_rcp_f32_e32 v170, v170
	v_rcp_f32_e32 v171, v171
	v_rcp_f32_e32 v172, v172
	v_rcp_f32_e32 v173, v173
	v_rcp_f32_e32 v174, v174
	v_rcp_f32_e32 v175, v175
	v_mul_f32_e32 v168, v30, v168
	v_mul_f32_e32 v169, v31, v169
	v_mul_f32_e32 v170, v32, v170
	v_mul_f32_e32 v171, v33, v171
	v_mul_f32_e32 v172, v22, v172
	v_mul_f32_e32 v173, v23, v173
	v_mul_f32_e32 v174, v24, v174
	v_mul_f32_e32 v175, v25, v175
	v_cvt_pk_bf16_f32 v184, v168, v169
	v_cvt_pk_bf16_f32 v185, v170, v171
	v_cvt_pk_bf16_f32 v186, v172, v173
	v_cvt_pk_bf16_f32 v187, v174, v175
	global_store_dwordx4 v[192:193], v[184:187], off
	s_mov_b64 s[20:21], 0xf2000
	v_lshl_add_u64 v[194:195], v[164:165], 0, s[20:21]
	v_mul_f32_e32 v176, s65, v14
	v_mul_f32_e32 v177, s65, v15
	v_mul_f32_e32 v178, s65, v16
	v_mul_f32_e32 v179, s65, v17
	v_mul_f32_e32 v180, s65, v6
	v_mul_f32_e32 v181, s65, v7
	v_mul_f32_e32 v182, s65, v8
	v_mul_f32_e32 v183, s65, v9
	v_exp_f32_e32 v176, v176
	v_exp_f32_e32 v177, v177
	v_exp_f32_e32 v178, v178
	v_exp_f32_e32 v179, v179
	v_exp_f32_e32 v180, v180
	v_exp_f32_e32 v181, v181
	v_exp_f32_e32 v182, v182
	v_exp_f32_e32 v183, v183
	v_mul_f32_e32 v14, v14, v10
	v_mul_f32_e32 v15, v15, v11
	v_mul_f32_e32 v16, v16, v12
	v_mul_f32_e32 v17, v17, v13
	v_mul_f32_e32 v6, v6, v2
	v_mul_f32_e32 v7, v7, v3
	v_mul_f32_e32 v8, v8, v4
	v_mul_f32_e32 v9, v9, v5
	v_add_f32_e32 v176, 1.0, v176
	v_add_f32_e32 v177, 1.0, v177
	v_add_f32_e32 v178, 1.0, v178
	v_add_f32_e32 v179, 1.0, v179
	v_add_f32_e32 v180, 1.0, v180
	v_add_f32_e32 v181, 1.0, v181
	v_add_f32_e32 v182, 1.0, v182
	v_add_f32_e32 v183, 1.0, v183
	v_rcp_f32_e32 v176, v176
	v_rcp_f32_e32 v177, v177
	v_rcp_f32_e32 v178, v178
	v_rcp_f32_e32 v179, v179
	v_rcp_f32_e32 v180, v180
	v_rcp_f32_e32 v181, v181
	v_rcp_f32_e32 v182, v182
	v_rcp_f32_e32 v183, v183
	v_mul_f32_e32 v176, v14, v176
	v_mul_f32_e32 v177, v15, v177
	v_mul_f32_e32 v178, v16, v178
	v_mul_f32_e32 v179, v17, v179
	v_mul_f32_e32 v180, v6, v180
	v_mul_f32_e32 v181, v7, v181
	v_mul_f32_e32 v182, v8, v182
	v_mul_f32_e32 v183, v9, v183
	v_cvt_pk_bf16_f32 v188, v176, v177
	v_cvt_pk_bf16_f32 v189, v178, v179
	v_cvt_pk_bf16_f32 v190, v180, v181
	v_cvt_pk_bf16_f32 v191, v182, v183
	global_store_dwordx4 v[194:195], v[188:191], off
	s_andn2_b64 vcc, exec, s[4:5]
	s_mov_b64 s[20:21], -1
	s_cbranch_vccnz .LBB0_190
	s_andn2_b64 vcc, exec, s[6:7]
	s_cbranch_vccnz .LBB0_189
	s_barrier
	s_branch .LBB0_189
